# first grid barrier: XCD census loads issued together instead of serialized
# speedup vs baseline: 1.0207x; 1.0051x over previous
.LBB0_65:
	v_readlane_b32 s2, v253, 4
	v_readlane_b32 s3, v253, 5
	s_waitcnt lgkmcnt(0)
	global_load_dword v2, v16, s[82:83] sc1
	global_load_dword v0, v16, s[82:83] offset:256 sc1
	global_load_dword v1, v16, s[82:83] offset:512 sc1
	global_load_dword v3, v16, s[82:83] offset:768 sc1
	global_load_dword v4, v16, s[82:83] offset:1024 sc1
	global_load_dword v5, v16, s[82:83] offset:1280 sc1
	global_load_dword v6, v16, s[82:83] offset:1536 sc1
	global_load_dword v7, v16, s[82:83] offset:1792 sc1
	global_load_dword v8, v16, s[82:83] offset:2048 sc1
	global_load_dword v9, v16, s[82:83] offset:2304 sc1
	global_load_dword v10, v16, s[82:83] offset:2560 sc1
	global_load_dword v11, v16, s[82:83] offset:2816 sc1
	global_load_dword v12, v16, s[82:83] offset:3072 sc1
	global_load_dword v13, v16, s[82:83] offset:3328 sc1
	global_load_dword v14, v16, s[82:83] offset:3584 sc1
	global_load_dword v15, v16, s[82:83] offset:3840 sc1
	s_mov_b64 s[4:5], -1
	s_mov_b64 s[2:3], -1
	s_waitcnt vmcnt(0)
	v_add_u32_e32 v17, v0, v2
	v_add_u32_e32 v17, v17, v1
	v_add_u32_e32 v17, v17, v3
	v_add_u32_e32 v17, v17, v4
	v_add_u32_e32 v17, v17, v5
	v_add_u32_e32 v17, v17, v6
	v_add_u32_e32 v17, v17, v7
	v_add_u32_e32 v17, v17, v8
	v_add_u32_e32 v17, v17, v9
	v_add_u32_e32 v17, v17, v10
	v_add_u32_e32 v17, v17, v11
	v_add_u32_e32 v17, v17, v12
	v_add_u32_e32 v17, v17, v13
	v_add_u32_e32 v17, v17, v14
	v_add_u32_e32 v17, v17, v15
	v_cmp_eq_u32_e32 vcc, s81, v17
	s_cbranch_vccnz .LBB0_64
	s_and_b32 s2, s8, 0xff
	s_cmp_eq_u32 s2, 0
	s_mov_b64 s[2:3], -1
	s_mov_b64 s[6:7], -1
	s_sleep 1
	s_cbranch_scc0 .LBB0_69
	global_load_dword v17, v16, s[28:29] sc1
	s_waitcnt vmcnt(0)
	v_cmp_eq_u32_e32 vcc, 0, v17
	s_cbranch_vccnz .LBB0_71
	s_mov_b64 s[6:7], 0
